# start-up load balance: context-row copy (4 loads per trip) and the two small table fills re-based onto workgroups 192..255, which idle while 0..191 compute the modulation vectors
# baseline (speedup 1.0000x reference)
; __device__ __forceinline__ int nblk_() { int t = gridDim.x; asm volatile("" : "+s"(t)); return t; }
; __device__ __forceinline__ void phase_pre(KArgs& a, LAS unsigned char* lds) {
;     ...
;         for (int task = bid; task < 4 * 48; task += nblk_()) {
;     ...
;     const size_t gt = (size_t)bid * 512 + tid, gn = (size_t)nblk_() * 512;
;     for (size_t i = gt; i < (size_t)NB * SEQ * DM / 4; i += gn) ((f32x4*)a.out)[i] = ((const f32x4*)a.x)[i];
;     for (size_t i = gt; i < (size_t)NB * CTXL * DM / 4; i += gn) ((f32x4*)(a.ws + OFF_XC))[i] = ((const f32x4*)a.ctx)[i];
;     f32x2* AP = (f32x2*)(a.ws + OFF_AP); f32x2* BB = (f32x2*)(a.ws + OFF_BB);
;     for (size_t e = gt; e < (size_t)4 * 2 * 32 * 64 * 33; e += gn) {
;         const int idx = (int)(e / 33), d = (int)(e - (size_t)idx * 33);
;         const float lr = fminf(a.lam_re[idx], -1e-4f), li = a.lam_im[idx], dt = expf(a.log_step[idx >> 6]);
;         const float mag = expf(lr * dt * (float)d); float sn, cs; sincosf(li * dt * (float)d, &sn, &cs);
;         AP[e] = (f32x2){mag * cs, mag * sn};
;     }
;     for (size_t e = gt; e < (size_t)4 * 2 * 32 * 64 * 16; e += gn) {
;         const int idx = (int)(e >> 4);
;         const float lr = fminf(a.lam_re[idx], -1e-4f), li = a.lam_im[idx], dt = expf(a.log_step[idx >> 6]);
;         const float mag = expf(lr * dt); float sn, cs; sincosf(li * dt, &sn, &cs);
;         const float nr = mag * cs - 1.f, ni = mag * sn, den = lr * lr + li * li;
;         const float qr = (nr * lr + ni * li) / den, qi = (ni * lr - nr * li) / den;
;         const float br = a.b_re[e], bi = a.b_im[e];
;         BB[e] = (f32x2){qr * br - qi * bi, qr * bi + qi * br};
;     }
.LBB0_17:
	v_readlane_b32 s0, v237, 0
	v_readlane_b32 s1, v237, 1
	s_load_dword s4, s[0:1], 0x10
	s_load_dword s5, s[0:1], 0x0
	s_ashr_i32 s23, s22, 31
	s_lshl_b64 s[0:1], s[22:23], 9
	v_lshl_add_u64 v[2:3], s[0:1], 0, v[34:35]
	s_waitcnt lgkmcnt(0)
	s_lshr_b32 s0, s4, 16
	s_cmp_lg_u32 s0, 0
	s_cselect_b64 s[0:1], -1, 0
	s_cmp_lg_u64 s[0:1], 0
	s_addc_u32 s24, s5, 0
	s_cmpk_lg_i32 s24, 0x100
	s_cbranch_scc1 .Lpre_keep
	s_movk_i32 s24, 64
	s_sub_i32 s22, s84, 0xc0
	s_cmp_lt_i32 s22, 0
	s_cselect_b32 s22, 0x10000, s22
	s_ashr_i32 s23, s22, 31
	s_lshl_b64 s[4:5], s[22:23], 9
	v_lshl_add_u64 v[2:3], s[4:5], 0, v[34:35]
.Lpre_keep:
	s_ashr_i32 s25, s24, 31
	s_mov_b64 s[4:5], 0x800000
	s_lshl_b64 s[0:1], s[24:25], 9
	v_cmp_gt_u64_e32 vcc, s[4:5], v[2:3]
	s_and_saveexec_b64 s[4:5], vcc
	s_branch .LBB0_20
.LBB0_20:
	s_or_b64 exec, exec, s[4:5]
	s_mov_b64 s[4:5], 0x7ffff
	v_cmp_lt_u64_e32 vcc, s[4:5], v[2:3]
	s_and_saveexec_b64 s[4:5], vcc
	s_xor_b64 s[4:5], exec, s[4:5]
	s_load_dwordx2 s[6:7], s[20:21], 0xe0
	s_or_saveexec_b64 s[4:5], s[4:5]
	s_waitcnt lgkmcnt(0)
	v_mov_b64_e32 v[4:5], s[6:7]
	s_xor_b64 exec, exec, s[4:5]
	s_cbranch_execz .LBB0_26
	s_load_dwordx2 s[6:7], s[20:21], 0x10
	s_load_dwordx2 s[8:9], s[20:21], 0xe0
	s_lshl_b64 s[12:13], s[22:23], 13
	v_lshl_add_u64 v[6:7], v[34:35], 4, s[12:13]
	s_lshl_b64 s[14:15], s[24:25], 13
	s_cmp_eq_u32 s0, 0x20000
	s_cbranch_scc1 .Lctx4_go
	s_cmp_lg_u32 s0, 0x8000
	s_cbranch_scc1 .Lctx_slow
.Lctx4_go:
	s_cmp_lg_u32 s1, 0
	s_cbranch_scc1 .Lctx_slow
	s_mov_b64 s[12:13], 0
	s_mov_b64 s[16:17], 0x7ffff
	v_mov_b64_e32 v[8:9], v[2:3]
.Lctx4:
	s_waitcnt lgkmcnt(0)
	v_lshl_add_u64 v[4:5], s[6:7], 0, v[6:7]
	v_lshl_add_u64 v[14:15], s[8:9], 0, v[6:7]
	global_load_dwordx4 v[10:13], v[4:5], off
	v_lshl_add_u64 v[4:5], v[4:5], 0, s[14:15]
	global_load_dwordx4 v[16:19], v[4:5], off
	v_lshl_add_u64 v[4:5], v[4:5], 0, s[14:15]
	global_load_dwordx4 v[20:23], v[4:5], off
	v_lshl_add_u64 v[4:5], v[4:5], 0, s[14:15]
	global_load_dwordx4 v[24:27], v[4:5], off
	v_lshl_add_u64 v[6:7], v[6:7], 0, s[14:15]
	v_lshl_add_u64 v[8:9], v[8:9], 0, s[0:1]
	v_lshl_add_u64 v[6:7], v[6:7], 0, s[14:15]
	v_lshl_add_u64 v[8:9], v[8:9], 0, s[0:1]
	v_lshl_add_u64 v[6:7], v[6:7], 0, s[14:15]
	v_lshl_add_u64 v[8:9], v[8:9], 0, s[0:1]
	v_lshl_add_u64 v[6:7], v[6:7], 0, s[14:15]
	v_lshl_add_u64 v[8:9], v[8:9], 0, s[0:1]
	v_cmp_lt_u64_e32 vcc, s[16:17], v[8:9]
	s_or_b64 s[12:13], vcc, s[12:13]
	s_waitcnt vmcnt(0)
	global_store_dwordx4 v[14:15], v[10:13], off
	v_lshl_add_u64 v[14:15], v[14:15], 0, s[14:15]
	global_store_dwordx4 v[14:15], v[16:19], off
	v_lshl_add_u64 v[14:15], v[14:15], 0, s[14:15]
	global_store_dwordx4 v[14:15], v[20:23], off
	v_lshl_add_u64 v[14:15], v[14:15], 0, s[14:15]
	global_store_dwordx4 v[14:15], v[24:27], off
	s_andn2_b64 exec, exec, s[12:13]
	s_cbranch_execnz .Lctx4
	s_or_b64 exec, exec, s[12:13]
	v_mov_b64_e32 v[4:5], s[8:9]
	s_branch .LBB0_26
.Lctx_slow:
	s_mov_b64 s[12:13], 0
	s_mov_b64 s[16:17], 0x7ffff
	v_mov_b64_e32 v[8:9], v[2:3]
